# attention loop: K/Q fragment ds_reads issued earlier (A-site at the loop latch before the barrier block, B-site before the bias update), Q addresses loop-invariant
# speedup vs baseline: 1.0163x; 1.0044x over previous
.LBB0_300:
	s_or_b64 exec, exec, s[4:5]
	s_lshl_b32 s4, s3, 8
	v_readlane_b32 s5, v245, 15
	s_lshl_b32 s69, s3, 2
	s_ashr_i32 s3, s2, 31
	s_add_i32 s68, s4, s5
	s_lshl_b64 s[2:3], s[2:3], 2
	s_sub_u32 s2, s7, s2
	v_mov_b32_e32 v3, s11
	v_mov_b32_e32 v8, s89
	s_subb_u32 s3, s33, s3
	v_mov_b32_e32 v175, 0
	s_waitcnt lgkmcnt(0)
	s_barrier
	ds_read_b128 v[4:7], v3
	ds_read_b128 v[8:11], v8
	v_and_b32_e32 v185, 31, v19
	v_lshrrev_b32_e32 v3, 1, v19
	v_lshlrev_b32_e32 v172, 2, v2
	v_lshlrev_b32_e32 v12, 7, v185
	v_bitop3_b32 v2, v3, v2, 7 bitop3:0x6c
	v_mul_f32_e32 v18, s12, v235
	v_lshl_add_u32 v186, v2, 4, v12
	v_or_b32_e32 v2, s68, v185
	v_cvt_f32_i32_e32 v3, v172
	v_mul_f32_e32 v173, 0x42800000, v18
	s_mov_b32 s56, 0x41600000
	v_cvt_f32_u32_e32 v2, v2
	v_div_scale_f32 v58, s[2:3], v173, v173, s56
	v_cvt_f32_u32_e32 v13, s4
	v_rcp_f32_e32 v60, v58
	s_waitcnt lgkmcnt(1)
	v_max_f32_e32 v5, v5, v5
	v_max_f32_e32 v4, v4, v4
	v_sub_f32_e32 v187, v3, v2
	v_max_f32_e32 v2, v4, v5
	v_max3_f32 v2, v2, v6, v7
	v_fma_f32 v3, -v58, v60, 1.0
	v_add_f32_e32 v176, v187, v13
	s_waitcnt lgkmcnt(0)
	v_max3_f32 v23, v2, v8, v9
	v_fmac_f32_e32 v60, v3, v60
	v_pk_add_f32 v[2:3], v[176:177], s[14:15] op_sel_hi:[0,1]
	v_max3_f32 v23, v23, v10, v11
	v_and_b32_e32 v24, 0x7fffffff, v2
	s_mov_b32 s2, 0xf800000
	v_and_b32_e32 v25, 0x7fffffff, v3
	v_pk_add_f32 v[12:13], v[176:177], s[22:23] op_sel_hi:[0,1]
	v_pk_add_f32 v[14:15], v[176:177], s[24:25] op_sel_hi:[0,1]
	v_pk_add_f32 v[16:17], v[176:177], s[26:27] op_sel_hi:[0,1]
	v_add_f32_e32 v26, 1.0, v176
	v_and_b32_e32 v11, 0x7fffffff, v13
	v_and_b32_e32 v10, 0x7fffffff, v12
	v_and_b32_e32 v13, 0x7fffffff, v15
	v_and_b32_e32 v12, 0x7fffffff, v14
	v_and_b32_e32 v15, 0x7fffffff, v17
	v_and_b32_e32 v14, 0x7fffffff, v16
	v_and_b32_e32 v22, 0x7fffffff, v176
	v_pk_mul_f32 v[16:17], v[14:15], v[18:19] op_sel_hi:[1,0] neg_lo:[0,1] neg_hi:[0,1]
	v_pk_add_f32 v[8:9], v[176:177], s[20:21] op_sel_hi:[0,1]
	v_and_b32_e32 v9, 0x7fffffff, v9
	v_and_b32_e32 v8, 0x7fffffff, v8
	v_readlane_b32 s55, v245, 28
	v_pk_add_f32 v[4:5], v[176:177], s[16:17] op_sel_hi:[0,1]
	v_pk_add_f32 v[6:7], v[176:177], s[18:19] op_sel_hi:[0,1]
	v_xor_b32_e32 v188, 32, v186
	v_and_b32_e32 v5, 0x7fffffff, v5
	v_and_b32_e32 v4, 0x7fffffff, v4
	v_and_b32_e32 v7, 0x7fffffff, v7
	v_and_b32_e32 v6, 0x7fffffff, v6
	v_add_u32_e32 v61, 0, v188
	v_add_u32_e32 v189, s52, v186
	v_add_u32_e32 v192, s52, v188
	v_div_scale_f32 v59, s[4:5], s56, v173, s56
	v_pk_add_f32 v[42:43], v[176:177], s[28:29] op_sel_hi:[0,1]
	v_pk_add_f32 v[44:45], v[176:177], s[30:31] op_sel_hi:[0,1]
	v_pk_add_f32 v[46:47], v[176:177], s[34:35] op_sel_hi:[0,1]
	v_pk_add_f32 v[48:49], v[176:177], s[36:37] op_sel_hi:[0,1]
	v_pk_add_f32 v[50:51], v[176:177], s[38:39] op_sel_hi:[0,1]
	v_pk_add_f32 v[52:53], v[176:177], s[40:41] op_sel_hi:[0,1]
	v_pk_add_f32 v[54:55], v[176:177], s[42:43] op_sel_hi:[0,1]
	v_pk_add_f32 v[56:57], v[176:177], s[44:45] op_sel_hi:[0,1]
	v_and_b32_e32 v57, 0x7fffffff, v57
	v_and_b32_e32 v56, 0x7fffffff, v56
	v_and_b32_e32 v55, 0x7fffffff, v55
	v_and_b32_e32 v54, 0x7fffffff, v54
	v_and_b32_e32 v53, 0x7fffffff, v53
	v_and_b32_e32 v52, 0x7fffffff, v52
	v_and_b32_e32 v51, 0x7fffffff, v51
	v_and_b32_e32 v50, 0x7fffffff, v50
	v_and_b32_e32 v49, 0x7fffffff, v49
	v_and_b32_e32 v48, 0x7fffffff, v48
	v_and_b32_e32 v47, 0x7fffffff, v47
	v_and_b32_e32 v46, 0x7fffffff, v46
	v_and_b32_e32 v45, 0x7fffffff, v45
	s_waitcnt vmcnt(4)
	v_mul_f32_e32 v2, v23, v249
	v_mul_f32_e32 v3, 0x4f800000, v2
	v_cmp_gt_f32_e32 vcc, s2, v2
	v_and_b32_e32 v23, 0x7fffffff, v26
	v_and_b32_e32 v44, 0x7fffffff, v44
	v_cndmask_b32_e32 v21, v2, v3, vcc
	v_sqrt_f32_e32 v27, v21
	v_pk_mul_f32 v[2:3], v[22:23], v[18:19] op_sel_hi:[1,0] neg_lo:[0,1] neg_hi:[0,1]
	v_and_b32_e32 v43, 0x7fffffff, v43
	v_and_b32_e32 v42, 0x7fffffff, v42
	v_add_u32_e32 v14, -1, v27
	v_add_u32_e32 v15, 1, v27
	v_fma_f32 v22, -v14, v27, v21
	v_fma_f32 v23, -v15, v27, v21
	v_cmp_ge_f32_e64 s[2:3], 0, v22
	v_pk_mul_f32 v[96:97], v[42:43], v[18:19] op_sel_hi:[1,0] neg_lo:[0,1] neg_hi:[0,1]
	v_pk_mul_f32 v[94:95], v[44:45], v[18:19] op_sel_hi:[1,0] neg_lo:[0,1] neg_hi:[0,1]
	v_cndmask_b32_e64 v14, v27, v14, s[2:3]
	v_cmp_lt_f32_e64 s[2:3], 0, v23
	v_pk_mul_f32 v[92:93], v[46:47], v[18:19] op_sel_hi:[1,0] neg_lo:[0,1] neg_hi:[0,1]
	v_pk_mul_f32 v[90:91], v[48:49], v[18:19] op_sel_hi:[1,0] neg_lo:[0,1] neg_hi:[0,1]
	v_cndmask_b32_e64 v14, v14, v15, s[2:3]
	v_mul_f32_e32 v15, 0x37800000, v14
	v_cndmask_b32_e32 v14, v14, v15, vcc
	v_cmp_class_f32_e32 vcc, v21, v232
	v_pk_mul_f32 v[88:89], v[50:51], v[18:19] op_sel_hi:[1,0] neg_lo:[0,1] neg_hi:[0,1]
	v_pk_mul_f32 v[86:87], v[52:53], v[18:19] op_sel_hi:[1,0] neg_lo:[0,1] neg_hi:[0,1]
	v_cndmask_b32_e32 v14, v14, v21, vcc
	v_mul_f32_e32 v21, 0x3f828f5c, v14
	v_add_f32_e32 v246, 0x42000000, v21
	s_nop 0
	v_readfirstlane_b32 s98, v246
	v_fmaak_f32 v22, 2.0, v21, 0x42000000
	v_div_scale_f32 v23, s[2:3], v18, v18, v22
	v_rcp_f32_e32 v26, v23
	v_pk_mul_f32 v[14:15], v[12:13], v[18:19] op_sel_hi:[1,0] neg_lo:[0,1] neg_hi:[0,1]
	v_div_scale_f32 v12, vcc, v22, v18, v22
	v_fma_f32 v13, -v23, v26, 1.0
	v_fmac_f32_e32 v26, v13, v26
	v_mul_f32_e32 v13, v12, v26
	v_fma_f32 v27, -v23, v13, v12
	v_fmac_f32_e32 v13, v27, v26
	v_fma_f32 v12, -v23, v13, v12
	v_div_fmas_f32 v12, v12, v26, v13
	v_div_fixup_f32 v22, v12, v18, v22
	v_cvt_i32_f32_e32 v23, v22
	v_cmp_gt_f32_e32 vcc, s90, v22
	v_pk_mul_f32 v[12:13], v[10:11], v[18:19] op_sel_hi:[1,0] neg_lo:[0,1] neg_hi:[0,1]
	v_pk_mul_f32 v[10:11], v[8:9], v[18:19] op_sel_hi:[1,0] neg_lo:[0,1] neg_hi:[0,1]
	v_readfirstlane_b32 s2, v23
	s_add_i32 s12, s2, 1
	s_and_b64 s[2:3], vcc, exec
	s_cselect_b32 s2, s12, 0x2000
	s_add_i32 s12, s2, 62
	s_add_i32 s2, s2, -2
	s_ashr_i32 s12, s12, 6
	s_ashr_i32 s2, s2, 6
	s_xor_b32 s3, s69, 60
	s_min_i32 s77, s69, s12
	s_add_i32 s2, s2, 1
	s_min_i32 s2, s3, s2
	s_add_i32 s82, s77, 4
	s_add_u32 s12, s80, 0x30000
	s_addc_u32 s13, s81, 0
	s_add_u32 s12, s80, 0x60000
	v_readlane_b32 s13, v245, 27
	s_addc_u32 s13, s81, 0
	v_add_u32_e32 v26, 0, v186
	v_readlane_b32 s12, v245, 29
	v_readlane_b32 s12, v245, 30
	v_pk_mul_f32 v[8:9], v[6:7], v[18:19] op_sel_hi:[1,0] neg_lo:[0,1] neg_hi:[0,1]
	v_pk_mul_f32 v[6:7], v[4:5], v[18:19] op_sel_hi:[1,0] neg_lo:[0,1] neg_hi:[0,1]
	v_pk_mul_f32 v[4:5], v[24:25], v[18:19] op_sel_hi:[1,0] neg_lo:[0,1] neg_hi:[0,1]
	ds_read_b128 v[22:25], v26
	ds_read_b128 v[26:29], v26 offset:4096
	ds_read_b128 v[30:33], v61
	ds_read_b128 v[34:37], v189
	ds_read_b128 v[38:41], v192
	s_waitcnt lgkmcnt(1)
	v_mfma_f32_32x32x16_bf16 v[98:113], v[22:25], v[34:37], v[2:17]
	v_mul_f32_e32 v22, v59, v60
	v_fma_f32 v23, -v58, v22, v59
	v_fmac_f32_e32 v22, v23, v60
	v_mul_f32_e64 v84, v54, -v18
	v_mul_f32_e64 v85, v55, -v18
	v_pk_mul_f32 v[82:83], v[56:57], v[18:19] op_sel_hi:[1,0] neg_lo:[0,1] neg_hi:[0,1]
	v_fma_f32 v23, -v58, v22, v59
	s_mov_b64 vcc, s[4:5]
	v_mfma_f32_32x32x16_bf16 v[82:97], v[26:29], v[34:37], v[82:97]
	v_div_fmas_f32 v26, v23, v60, v22
	ds_read_b128 v[22:25], v61 offset:4096
	v_div_fixup_f32 v26, v26, v173, s56
	v_cmp_gt_f32_e32 vcc, s24, v21
	s_add_i32 s83, s82, s2
	s_cmp_lt_i32 s83, 1
	v_cndmask_b32_e32 v21, 0, v26, vcc
	s_waitcnt lgkmcnt(1)
	v_mfma_f32_32x32x16_bf16 v[98:113], v[30:33], v[38:41], v[98:113]
	v_min_f32_e32 v21, 0x42800000, v21
	s_nop 0
	v_readfirstlane_b32 s3, v21
	s_waitcnt lgkmcnt(0)
	v_mfma_f32_32x32x16_bf16 v[82:97], v[22:25], v[38:41], v[82:97]
	s_cbranch_scc1 .LBB0_350
	v_lshrrev_b32_e32 v21, 2, v19
	v_lshlrev_b32_e32 v19, 1, v19
	v_cvt_i32_f32_e32 v193, s3
	v_and_or_b32 v21, v21, 3, v172
	v_and_or_b32 v19, v19, 32, v20
	v_readfirstlane_b32 s99, v193
	v_lshl_or_b32 v19, v21, 6, v19
	v_mov_b32_e32 v50, v1
	v_mov_b32_e32 v51, v1
	v_mov_b32_e32 v64, v1
	v_mov_b32_e32 v65, v1
	v_xor_b32_e32 v178, 0x80000000, v18
	v_add_u32_e32 v195, 0x2000, v19
	v_mul_f32_e32 v196, 0x42000000, v18
	v_mul_f32_e32 v197, 0xc2000000, v18
	s_add_i32 s86, s2, s77
	v_mov_b32_e32 v52, v1
	v_mov_b32_e32 v53, v1
	v_mov_b32_e32 v54, v1
	v_mov_b32_e32 v55, v1
	v_mov_b32_e32 v56, v1
	v_mov_b32_e32 v57, v1
	v_mov_b32_e32 v58, v1
	v_mov_b32_e32 v59, v1
	v_mov_b32_e32 v60, v1
	v_mov_b32_e32 v61, v1
	v_mov_b32_e32 v62, v1
	v_mov_b32_e32 v63, v1
	v_mov_b64_e32 v[18:19], v[50:51]
	v_mov_b64_e32 v[80:81], v[64:65]
	v_mov_b64_e32 v[34:35], v[50:51]
	v_mov_b32_e32 v180, v178
	v_mov_b32_e32 v181, v178
	v_xor_b32_e32 v194, 64, v186
	s_sub_i32 s84, s69, s77
	s_or_b32 s85, s69, 3
	v_xor_b32_e32 v198, 0x60, v186
	s_add_i32 s86, s86, 4
	s_add_i32 s87, s77, 3
	s_mov_b32 s88, 0
	v_mov_b32_e32 v174, v1
	v_mov_b32_e32 v175, v1
	v_mov_b32_e32 v182, 0
	s_mov_b32 s89, s69
	v_mov_b64_e32 v[20:21], v[52:53]
	v_mov_b64_e32 v[22:23], v[54:55]
	v_mov_b64_e32 v[24:25], v[56:57]
	v_mov_b64_e32 v[26:27], v[58:59]
	v_mov_b64_e32 v[28:29], v[60:61]
	v_mov_b64_e32 v[30:31], v[62:63]
	v_mov_b64_e32 v[32:33], v[64:65]
	v_mov_b64_e32 v[78:79], v[62:63]
	v_mov_b64_e32 v[76:77], v[60:61]
	v_mov_b64_e32 v[74:75], v[58:59]
	v_mov_b64_e32 v[72:73], v[56:57]
	v_mov_b64_e32 v[70:71], v[54:55]
	v_mov_b64_e32 v[68:69], v[52:53]
	v_mov_b64_e32 v[66:67], v[50:51]
	v_mov_b64_e32 v[36:37], v[52:53]
	v_mov_b64_e32 v[38:39], v[54:55]
	v_mov_b64_e32 v[40:41], v[56:57]
	v_mov_b64_e32 v[42:43], v[58:59]
	v_mov_b64_e32 v[44:45], v[60:61]
	v_mov_b64_e32 v[46:47], v[62:63]
	v_mov_b64_e32 v[48:49], v[64:65]
	v_add_u32_e32 v254, s52, v194
	v_add_u32_e32 v255, s52, v198
	v_add_u32_e32 v114, s88, v194
	ds_read_b128 v[158:161], v114
	ds_read_b128 v[150:153], v114 offset:4096
	v_add_u32_e32 v114, s88, v198
	ds_read_b128 v[154:157], v114
	ds_read_b128 v[146:149], v114 offset:4096
	ds_read_b128 v[166:169], v254
	ds_read_b128 v[162:165], v255
	s_mov_b32 s90, 0
	s_add_i32 s2, s90, 2
	s_cmp_ge_i32 s2, s83
	s_mov_b64 s[2:3], -1
	s_cbranch_scc0 .LBB0_303

.LBB0_310:
	s_cmp_lt_i32 s90, s82
	s_cselect_b64 s[4:5], -1, 0
	s_cmp_lt_u32 s90, 4
	s_cselect_b64 s[2:3], -1, 0
	s_mov_b64 s[12:13], -1
	s_and_b64 vcc, exec, s[2:3]
	s_cbranch_vccnz .LBB0_312
	v_cndmask_b32_e64 v114, v197, v196, s[4:5]
	v_pk_add_f32 v[128:129], v[114:115], v[16:17] op_sel_hi:[0,1]
	v_pk_add_f32 v[126:127], v[114:115], v[14:15] op_sel_hi:[0,1]
	v_pk_add_f32 v[124:125], v[114:115], v[12:13] op_sel_hi:[0,1]
	v_pk_add_f32 v[122:123], v[114:115], v[10:11] op_sel_hi:[0,1]
	v_pk_add_f32 v[120:121], v[114:115], v[8:9] op_sel_hi:[0,1]
	v_pk_add_f32 v[118:119], v[114:115], v[6:7] op_sel_hi:[0,1]
	v_pk_add_f32 v[116:117], v[114:115], v[4:5] op_sel_hi:[0,1]
	v_pk_add_f32 v[114:115], v[114:115], v[2:3] op_sel_hi:[0,1]
	s_mov_b64 s[12:13], 0

.LBB0_324:
	s_add_i32 s100, s88, 0x4000
	s_and_b32 s100, s100, 0xffff
	v_add_u32_e32 v82, s100, v186
	ds_read_b128 v[162:165], v82
	ds_read_b128 v[150:153], v82 offset:4096
	v_add_u32_e32 v82, s100, v188
	ds_read_b128 v[154:157], v82
	ds_read_b128 v[146:149], v82 offset:4096
	ds_read_b128 v[166:169], v189
	ds_read_b128 v[158:161], v192
	v_sub_f32_e32 v17, v17, v173
	v_sub_f32_e32 v16, v16, v173
	v_sub_f32_e32 v15, v15, v173
	v_sub_f32_e32 v14, v14, v173
	v_sub_f32_e32 v13, v13, v173
	v_sub_f32_e32 v12, v12, v173
	v_sub_f32_e32 v11, v11, v173
	v_sub_f32_e32 v10, v10, v173
	v_sub_f32_e32 v9, v9, v173
	v_sub_f32_e32 v8, v8, v173
	v_sub_f32_e32 v7, v7, v173
	v_sub_f32_e32 v6, v6, v173
	v_sub_f32_e32 v5, v5, v173
	v_sub_f32_e32 v4, v4, v173
	v_sub_f32_e32 v3, v3, v173
	v_sub_f32_e32 v2, v2, v173
	s_add_i32 s12, s90, 1
	s_cbranch_execnz .LBB0_323

.Lqk_B_noreads:
	s_cmp_lt_u32 s90, 3
	s_mov_b64 s[2:3], -1
	s_cbranch_scc1 .LBB0_336
	s_cmp_lt_i32 s12, s82
	s_cselect_b64 vcc, -1, 0
	v_cndmask_b32_e32 v82, v197, v196, vcc
	v_pk_add_f32 v[96:97], v[82:83], v[16:17] op_sel_hi:[0,1]
	v_pk_add_f32 v[94:95], v[82:83], v[14:15] op_sel_hi:[0,1]
	v_pk_add_f32 v[92:93], v[82:83], v[12:13] op_sel_hi:[0,1]
	v_pk_add_f32 v[90:91], v[82:83], v[10:11] op_sel_hi:[0,1]
	v_pk_add_f32 v[88:89], v[82:83], v[8:9] op_sel_hi:[0,1]
	v_pk_add_f32 v[86:87], v[82:83], v[6:7] op_sel_hi:[0,1]
	v_pk_add_f32 v[84:85], v[82:83], v[4:5] op_sel_hi:[0,1]
	v_pk_add_f32 v[82:83], v[82:83], v[2:3] op_sel_hi:[0,1]
	s_mov_b64 s[2:3], 0

.Ldyn_post_back:
	s_mov_b32 s90, s12
	v_add_u32_e32 v114, s88, v194
	ds_read_b128 v[158:161], v114
	ds_read_b128 v[150:153], v114 offset:4096
	v_add_u32_e32 v114, s88, v198
	ds_read_b128 v[154:157], v114
	ds_read_b128 v[146:149], v114 offset:4096
	ds_read_b128 v[166:169], v254
	ds_read_b128 v[162:165], v255
	s_add_i32 s2, s90, 2
	s_cmp_ge_i32 s2, s83
	s_mov_b64 s[2:3], -1
	s_cbranch_scc1 .LBB0_302
	s_branch .LBB0_303

	.amdhsa_kernel _Z14fwd_megakernel4Args
		.amdhsa_group_segment_fixed_size 0
		.amdhsa_private_segment_fixed_size 0
		.amdhsa_kernarg_size 392
		.amdhsa_user_sgpr_count 2
		.amdhsa_user_sgpr_dispatch_ptr 0
		.amdhsa_user_sgpr_queue_ptr 0
		.amdhsa_user_sgpr_kernarg_segment_ptr 1
		.amdhsa_user_sgpr_dispatch_id 0
		.amdhsa_user_sgpr_kernarg_preload_length 0
		.amdhsa_user_sgpr_kernarg_preload_offset 0
		.amdhsa_user_sgpr_private_segment_size 0
		.amdhsa_uses_dynamic_stack 0
		.amdhsa_enable_private_segment 0
		.amdhsa_system_sgpr_workgroup_id_x 1
		.amdhsa_system_sgpr_workgroup_id_y 0
		.amdhsa_system_sgpr_workgroup_id_z 0
		.amdhsa_system_sgpr_workgroup_info 0
		.amdhsa_system_vgpr_workitem_id 2
		.amdhsa_next_free_vgpr 256
		.amdhsa_next_free_sgpr 102
		.amdhsa_accum_offset 256
		.amdhsa_reserve_vcc 1
		.amdhsa_float_round_mode_32 0
		.amdhsa_float_round_mode_16_64 0
		.amdhsa_float_denorm_mode_32 3
		.amdhsa_float_denorm_mode_16_64 3
		.amdhsa_dx10_clamp 1
		.amdhsa_ieee_mode 1
		.amdhsa_fp16_overflow 0
		.amdhsa_tg_split 0
		.amdhsa_exception_fp_ieee_invalid_op 0
		.amdhsa_exception_fp_denorm_src 0
		.amdhsa_exception_fp_ieee_div_zero 0
		.amdhsa_exception_fp_ieee_overflow 0
		.amdhsa_exception_fp_ieee_underflow 0
		.amdhsa_exception_fp_ieee_inexact 0
		.amdhsa_exception_int_div_zero 0
	.end_amdhsa_kernel

amdhsa.kernels:
  - .agpr_count:     0
    .args:
      - .offset:         0
        .size:           136
        .value_kind:     by_value
      - .offset:         136
        .size:           4
        .value_kind:     hidden_block_count_x
      - .offset:         140
        .size:           4
        .value_kind:     hidden_block_count_y
      - .offset:         144
        .size:           4
        .value_kind:     hidden_block_count_z
      - .offset:         148
        .size:           2
        .value_kind:     hidden_group_size_x
      - .offset:         150
        .size:           2
        .value_kind:     hidden_group_size_y
      - .offset:         152
        .size:           2
        .value_kind:     hidden_group_size_z
      - .offset:         154
        .size:           2
        .value_kind:     hidden_remainder_x
      - .offset:         156
        .size:           2
        .value_kind:     hidden_remainder_y
      - .offset:         158
        .size:           2
        .value_kind:     hidden_remainder_z
      - .offset:         176
        .size:           8
        .value_kind:     hidden_global_offset_x
      - .offset:         184
        .size:           8
        .value_kind:     hidden_global_offset_y
      - .offset:         192
        .size:           8
        .value_kind:     hidden_global_offset_z
      - .offset:         200
        .size:           2
        .value_kind:     hidden_grid_dims
      - .offset:         224
        .size:           8
        .value_kind:     hidden_multigrid_sync_arg
      - .offset:         256
        .size:           4
        .value_kind:     hidden_dynamic_lds_size
    .group_segment_fixed_size: 0
    .kernarg_segment_align: 8
    .kernarg_segment_size: 392
    .language:       OpenCL C
    .language_version:
      - 2
      - 0
    .max_flat_workgroup_size: 512
    .name:           _Z14fwd_megakernel4Args
    .private_segment_fixed_size: 0
    .sgpr_count:     108
    .sgpr_spill_count: 98
    .symbol:         _Z14fwd_megakernel4Args.kd
    .uniform_work_group_size: 1
    .uses_dynamic_stack: false
    .vgpr_count:     256
    .vgpr_spill_count: 0
    .wavefront_size: 64
